# iv2 without the extra in-flight barrier polls: with L1-only acquires the leftover poll was what the barrier exit waited for
# baseline (speedup 1.0000x reference)
.LBB0_532:
	v_mov_b32_e32 v2, 0
	global_load_dword v3, v2, s[6:7] sc1
	s_mov_b32 s0, 1
	s_waitcnt vmcnt(0)
	v_and_b32_e32 v9, 0xff, v3
	v_cmp_lt_u32_e32 vcc, 1, v9
	s_cbranch_vccz .LBB0_534
	s_branch .LBB0_542
.LBB0_533:
	s_andn2_b64 vcc, exec, s[4:5]
	s_cbranch_vccz .LBB0_540

.LBB0_536:
	global_load_dword v3, v2, s[6:7] sc1
	s_add_i32 s0, s0, 1
	s_mov_b64 s[8:9], -1
	s_waitcnt vmcnt(0)
	v_and_b32_e32 v9, 0xff, v3
	v_cmp_lt_u32_e64 s[4:5], 1, v9
	s_branch .LBB0_533
